# work queue: first 128 weight-copy items ahead of the decode items so the side workgroups absorb them before phase 3 ends
# baseline (speedup 1.0000x reference)
.LBB0_517:
	s_or_b64 exec, exec, s[0:1]
	s_waitcnt lgkmcnt(0)
	s_barrier
	ds_read_b32 v1, v232
	s_mov_b64 s[0:1], -1
	s_waitcnt lgkmcnt(0)
	s_barrier
	v_readfirstlane_b32 s60, v1
	s_cmpk_gt_i32 s60, 0x58f
	s_cbranch_scc1 .Lp3d_chk
	s_cmpk_lt_i32 s60, 0x80
	s_cbranch_scc0 .Lq_1
	s_addk_i32 s60, 0x4a0
	s_branch .Lp3d_go
.Lq_1:
	s_cmpk_lt_i32 s60, 0x100
	s_cbranch_scc0 .Lq_2
	s_addk_i32 s60, 0xff80
	s_branch .Lp3d_go
.Lq_2:
	s_cmpk_lt_i32 s60, 0x170
	s_cbranch_scc0 .Lp3d_sub
	s_addk_i32 s60, 0x420
	s_branch .Lp3d_go
